# XCC-local barrier rewritten: per-WG flag words in one line per XCC, 32-lane poll (no returning atomic, no release hop)
# baseline (speedup 1.0000x reference)
.LBB0_339:
	s_or_b64 exec, exec, s[2:3]
	s_add_i32 s0, 0, 0x20178
	v_mov_b32_e32 v2, s0
	s_waitcnt lgkmcnt(0)
	s_barrier
	ds_read_b32 v2, v2
	s_waitcnt lgkmcnt(0)
	v_cmp_eq_u32_e32 vcc, 0, v2
	v_cmp_ne_u32_e64 s[0:1], 0, v2
	s_cbranch_vccnz .LBB0_341
	s_add_i32 s2, 0, 0x20174
	v_mov_b32_e32 v2, s2
	s_add_i32 s2, 0, 0x20170
	ds_read_b32 v2, v2
	v_mov_b32_e32 v3, s2
	ds_read_b32 v3, v3
	s_waitcnt lgkmcnt(1)
	v_readfirstlane_b32 s2, v2
	s_lshl_b32 s4, s2, 5
	s_waitcnt lgkmcnt(0)
	v_readfirstlane_b32 s3, v3
	s_add_i32 s66, s4, s3
	s_and_b32 s101, s66, 31
	s_lshl_b32 s3, s3, 3
	s_add_i32 s28, s3, s2

.LBB0_458:
	s_cmp_gt_i32 s89, 2
	s_cselect_b64 s[0:1], -1, 0
	s_and_b64 s[2:3], s[4:5], s[0:1]
	s_andn2_b64 vcc, exec, s[2:3]
	s_cbranch_vccnz .LBB0_476
	s_waitcnt vmcnt(0)
	v_cmp_gt_u32_e32 vcc, 32, v0
	s_waitcnt vmcnt(0)
	s_barrier
	s_and_saveexec_b64 s[2:3], vcc
	s_cbranch_execz .LBB0_475
	v_readlane_b32 s4, v253, 9
	s_lshl_b32 s4, s4, 8
	v_readlane_b32 s6, v253, 3
	v_readlane_b32 s7, v253, 4
	s_add_u32 s4, s6, s4
	s_addc_u32 s5, s7, 0
	s_add_u32 s4, s4, 0x20000
	s_addc_u32 s5, s5, 0
	s_add_i32 s101, s101, 0x100
	s_and_b32 s6, s101, 31
	s_lshr_b32 s7, s101, 8
	v_lshlrev_b32_e32 v2, 2, v0
	v_mov_b32_e32 v3, 1
	v_cmp_eq_u32_e32 vcc, s6, v0
	s_and_saveexec_b64 s[8:9], vcc
	global_atomic_add v2, v3, s[4:5]
	s_or_b64 exec, exec, s[8:9]
	buffer_inv sc1
	s_mov_b32 s6, 0
.Lxb_poll_13:
	global_load_dword v4, v2, s[4:5] sc1
	s_waitcnt vmcnt(0)
	v_cmp_gt_u32_e32 vcc, s7, v4
	s_nop 1
	s_cmp_eq_u64 vcc, 0
	s_cbranch_scc1 .Lxb_done_13
	s_add_i32 s6, s6, 1
	s_sleep 1
	s_cmp_lt_u32 s6, 0x40000
	s_cbranch_scc1 .Lxb_poll_13
.Lxb_done_13:
	s_waitcnt vmcnt(0)
.LBB0_475:
	s_or_b64 exec, exec, s[2:3]
	s_barrier

.LBB0_502:
	s_cmp_gt_i32 s89, 3
	s_cselect_b64 s[2:3], -1, 0
	s_and_b64 s[0:1], s[0:1], s[2:3]
	s_andn2_b64 vcc, exec, s[0:1]
	s_cbranch_vccnz .LBB0_520
	s_waitcnt vmcnt(0)
	v_cmp_gt_u32_e32 vcc, 32, v0
	s_waitcnt vmcnt(0)
	s_barrier
	s_and_saveexec_b64 s[0:1], vcc
	s_cbranch_execz .LBB0_519
	v_readlane_b32 s4, v253, 9
	s_lshl_b32 s4, s4, 8
	v_readlane_b32 s6, v253, 3
	v_readlane_b32 s7, v253, 4
	s_add_u32 s4, s6, s4
	s_addc_u32 s5, s7, 0
	s_add_u32 s4, s4, 0x20000
	s_addc_u32 s5, s5, 0
	s_add_i32 s101, s101, 0x100
	s_and_b32 s6, s101, 31
	s_lshr_b32 s7, s101, 8
	v_lshlrev_b32_e32 v2, 2, v0
	v_mov_b32_e32 v3, 1
	v_cmp_eq_u32_e32 vcc, s6, v0
	s_and_saveexec_b64 s[8:9], vcc
	global_atomic_add v2, v3, s[4:5]
	s_or_b64 exec, exec, s[8:9]
	buffer_inv sc1
	s_mov_b32 s6, 0

.Lxb_done_12:
	s_waitcnt vmcnt(0)
.LBB0_519:
	s_or_b64 exec, exec, s[0:1]
	s_barrier

.LBB0_526:
	s_cmp_gt_i32 s89, 4
	s_cselect_b64 s[0:1], -1, 0
	s_and_b64 s[2:3], s[6:7], s[0:1]
	s_andn2_b64 vcc, exec, s[2:3]
	s_cbranch_vccnz .LBB0_544
	s_waitcnt vmcnt(0)
	v_cmp_gt_u32_e32 vcc, 32, v0
	s_waitcnt vmcnt(0)
	s_barrier
	s_and_saveexec_b64 s[2:3], vcc
	s_cbranch_execz .LBB0_543
	v_readlane_b32 s4, v253, 9
	s_lshl_b32 s4, s4, 8
	v_readlane_b32 s6, v253, 3
	v_readlane_b32 s7, v253, 4
	s_add_u32 s4, s6, s4
	s_addc_u32 s5, s7, 0
	s_add_u32 s4, s4, 0x20000
	s_addc_u32 s5, s5, 0
	s_add_i32 s101, s101, 0x100
	s_and_b32 s6, s101, 31
	s_lshr_b32 s7, s101, 8
	v_lshlrev_b32_e32 v2, 2, v0
	v_mov_b32_e32 v3, 1
	v_cmp_eq_u32_e32 vcc, s6, v0
	s_and_saveexec_b64 s[8:9], vcc
	global_atomic_add v2, v3, s[4:5]
	s_or_b64 exec, exec, s[8:9]
	buffer_inv sc1
	s_mov_b32 s6, 0

.Lxb_done_11:
	s_waitcnt vmcnt(0)
.LBB0_543:
	s_or_b64 exec, exec, s[2:3]
	s_barrier

.LBB0_605:
	s_cmp_gt_i32 s89, 5
	s_cselect_b64 s[0:1], -1, 0
	s_and_b64 s[2:3], s[4:5], s[0:1]
	s_andn2_b64 vcc, exec, s[2:3]
	s_cbranch_vccnz .LBB0_623
	s_waitcnt vmcnt(0)
	v_cmp_gt_u32_e32 vcc, 32, v0
	s_waitcnt vmcnt(0)
	s_barrier
	s_and_saveexec_b64 s[2:3], vcc
	s_cbranch_execz .LBB0_622
	v_readlane_b32 s4, v253, 9
	s_lshl_b32 s4, s4, 8
	v_readlane_b32 s6, v253, 3
	v_readlane_b32 s7, v253, 4
	s_add_u32 s4, s6, s4
	s_addc_u32 s5, s7, 0
	s_add_u32 s4, s4, 0x20000
	s_addc_u32 s5, s5, 0
	s_add_i32 s101, s101, 0x100
	s_and_b32 s6, s101, 31
	s_lshr_b32 s7, s101, 8
	v_lshlrev_b32_e32 v2, 2, v0
	v_mov_b32_e32 v3, 1
	v_cmp_eq_u32_e32 vcc, s6, v0
	s_and_saveexec_b64 s[8:9], vcc
	global_atomic_add v2, v3, s[4:5]
	s_or_b64 exec, exec, s[8:9]
	buffer_inv sc1
	s_mov_b32 s6, 0

.Lxb_done_10:
	s_waitcnt vmcnt(0)
.LBB0_622:
	s_or_b64 exec, exec, s[2:3]
	s_barrier

.LBB0_717:
	s_cmp_gt_i32 s89, 6
	v_readlane_b32 s2, v252, 12
	s_cselect_b64 s[0:1], -1, 0
	v_readlane_b32 s3, v252, 13
	s_and_b64 s[2:3], s[2:3], s[0:1]
	s_andn2_b64 vcc, exec, s[2:3]
	s_cbranch_vccnz .LBB0_735
	s_waitcnt vmcnt(0)
	v_cmp_gt_u32_e32 vcc, 32, v0
	s_waitcnt vmcnt(0)
	s_barrier
	s_and_saveexec_b64 s[2:3], vcc
	s_cbranch_execz .LBB0_734
	v_readlane_b32 s4, v253, 9
	s_lshl_b32 s4, s4, 8
	v_readlane_b32 s6, v253, 3
	v_readlane_b32 s7, v253, 4
	s_add_u32 s4, s6, s4
	s_addc_u32 s5, s7, 0
	s_add_u32 s4, s4, 0x20000
	s_addc_u32 s5, s5, 0
	s_add_i32 s101, s101, 0x100
	s_and_b32 s6, s101, 31
	s_lshr_b32 s7, s101, 8
	v_lshlrev_b32_e32 v1, 2, v0
	v_mov_b32_e32 v2, 1
	v_cmp_eq_u32_e32 vcc, s6, v0
	s_and_saveexec_b64 s[8:9], vcc
	global_atomic_add v1, v2, s[4:5]
	s_or_b64 exec, exec, s[8:9]
	buffer_inv sc1
	s_mov_b32 s6, 0
.Lxb_poll_9:
	global_load_dword v4, v1, s[4:5] sc1
	s_waitcnt vmcnt(0)
	v_cmp_gt_u32_e32 vcc, s7, v4
	s_nop 1
	s_cmp_eq_u64 vcc, 0
	s_cbranch_scc1 .Lxb_done_9
	s_add_i32 s6, s6, 1
	s_sleep 1
	s_cmp_lt_u32 s6, 0x40000
	s_cbranch_scc1 .Lxb_poll_9
.Lxb_done_9:
	s_waitcnt vmcnt(0)
.LBB0_734:
	s_or_b64 exec, exec, s[2:3]
	s_barrier

.LBB0_739:
	s_cmp_gt_i32 s89, 7
	s_cselect_b64 s[2:3], -1, 0
	s_and_b64 s[0:1], s[0:1], s[2:3]
	s_andn2_b64 vcc, exec, s[0:1]
	s_cbranch_vccnz .LBB0_757
	s_waitcnt vmcnt(0)
	v_cmp_gt_u32_e32 vcc, 32, v0
	s_waitcnt vmcnt(0)
	s_barrier
	s_and_saveexec_b64 s[0:1], vcc
	s_cbranch_execz .LBB0_756
	v_readlane_b32 s4, v253, 9
	s_lshl_b32 s4, s4, 8
	v_readlane_b32 s6, v253, 3
	v_readlane_b32 s7, v253, 4
	s_add_u32 s4, s6, s4
	s_addc_u32 s5, s7, 0
	s_add_u32 s4, s4, 0x20000
	s_addc_u32 s5, s5, 0
	s_add_i32 s101, s101, 0x100
	s_and_b32 s6, s101, 31
	s_lshr_b32 s7, s101, 8
	v_lshlrev_b32_e32 v1, 2, v0
	v_mov_b32_e32 v2, 1
	v_cmp_eq_u32_e32 vcc, s6, v0
	s_and_saveexec_b64 s[8:9], vcc
	global_atomic_add v1, v2, s[4:5]
	s_or_b64 exec, exec, s[8:9]
	buffer_inv sc1
	s_mov_b32 s6, 0

.Lxb_done_8:
	s_waitcnt vmcnt(0)
.LBB0_756:
	s_or_b64 exec, exec, s[0:1]
	s_barrier

.LBB0_1061:
	s_cmp_gt_i32 s89, 8
	s_cselect_b64 s[0:1], -1, 0
	s_and_b64 s[2:3], s[38:39], s[0:1]
	s_andn2_b64 vcc, exec, s[2:3]
	s_cbranch_vccnz .LBB0_1079
	s_waitcnt vmcnt(0)
	v_cmp_gt_u32_e32 vcc, 32, v0
	s_waitcnt vmcnt(0)
	s_barrier
	s_and_saveexec_b64 s[2:3], vcc
	s_cbranch_execz .LBB0_1078
	v_readlane_b32 s4, v253, 9
	s_lshl_b32 s4, s4, 8
	v_readlane_b32 s6, v253, 3
	v_readlane_b32 s7, v253, 4
	s_add_u32 s4, s6, s4
	s_addc_u32 s5, s7, 0
	s_add_u32 s4, s4, 0x20000
	s_addc_u32 s5, s5, 0
	s_add_i32 s101, s101, 0x100
	s_and_b32 s6, s101, 31
	s_lshr_b32 s7, s101, 8
	v_lshlrev_b32_e32 v1, 2, v0
	v_mov_b32_e32 v2, 1
	v_cmp_eq_u32_e32 vcc, s6, v0
	s_and_saveexec_b64 s[8:9], vcc
	global_atomic_add v1, v2, s[4:5]
	s_or_b64 exec, exec, s[8:9]
	buffer_inv sc1
	s_mov_b32 s6, 0

.Lxb_done_7:
	s_waitcnt vmcnt(0)
.LBB0_1078:
	s_or_b64 exec, exec, s[2:3]
	s_barrier

.LBB0_1105:
	s_cmp_gt_i32 s89, 9
	s_cselect_b64 s[2:3], -1, 0
	s_and_b64 s[0:1], s[0:1], s[2:3]
	s_andn2_b64 vcc, exec, s[0:1]
	s_cbranch_vccnz .LBB0_1123
	s_waitcnt vmcnt(0)
	v_cmp_gt_u32_e32 vcc, 32, v0
	s_waitcnt vmcnt(0)
	s_barrier
	s_and_saveexec_b64 s[0:1], vcc
	s_cbranch_execz .LBB0_1122
	v_readlane_b32 s4, v253, 9
	s_lshl_b32 s4, s4, 8
	v_readlane_b32 s6, v253, 3
	v_readlane_b32 s7, v253, 4
	s_add_u32 s4, s6, s4
	s_addc_u32 s5, s7, 0
	s_add_u32 s4, s4, 0x20000
	s_addc_u32 s5, s5, 0
	s_add_i32 s101, s101, 0x100
	s_and_b32 s6, s101, 31
	s_lshr_b32 s7, s101, 8
	v_lshlrev_b32_e32 v1, 2, v0
	v_mov_b32_e32 v2, 1
	v_cmp_eq_u32_e32 vcc, s6, v0
	s_and_saveexec_b64 s[8:9], vcc
	global_atomic_add v1, v2, s[4:5]
	s_or_b64 exec, exec, s[8:9]
	buffer_inv sc1
	s_mov_b32 s6, 0

.Lxb_done_6:
	s_waitcnt vmcnt(0)
.LBB0_1122:
	s_or_b64 exec, exec, s[0:1]
	s_barrier

.LBB0_1140:
	s_cmp_gt_i32 s89, 10
	s_cselect_b64 s[0:1], -1, 0
	s_and_b64 s[2:3], s[6:7], s[0:1]
	s_andn2_b64 vcc, exec, s[2:3]
	s_cbranch_vccnz .LBB0_1158
	s_waitcnt vmcnt(0)
	v_cmp_gt_u32_e32 vcc, 32, v0
	s_waitcnt vmcnt(0)
	s_barrier
	s_and_saveexec_b64 s[2:3], vcc
	s_cbranch_execz .LBB0_1157
	v_readlane_b32 s4, v253, 9
	s_lshl_b32 s4, s4, 8
	v_readlane_b32 s6, v253, 3
	v_readlane_b32 s7, v253, 4
	s_add_u32 s4, s6, s4
	s_addc_u32 s5, s7, 0
	s_add_u32 s4, s4, 0x20000
	s_addc_u32 s5, s5, 0
	s_add_i32 s101, s101, 0x100
	s_and_b32 s6, s101, 31
	s_lshr_b32 s7, s101, 8
	v_lshlrev_b32_e32 v1, 2, v0
	v_mov_b32_e32 v2, 1
	v_cmp_eq_u32_e32 vcc, s6, v0
	s_and_saveexec_b64 s[8:9], vcc
	global_atomic_add v1, v2, s[4:5]
	s_or_b64 exec, exec, s[8:9]
	buffer_inv sc1
	s_mov_b32 s6, 0

.Lxb_done_5:
	s_waitcnt vmcnt(0)
.LBB0_1157:
	s_or_b64 exec, exec, s[2:3]
	s_barrier

.LBB0_1202:
	s_cmp_gt_i32 s89, 11
	s_cselect_b64 s[0:1], -1, 0
	v_readlane_b32 s8, v253, 36
	s_and_b64 s[2:3], s[6:7], s[0:1]
	v_readlane_b32 s18, v253, 46
	v_readlane_b32 s19, v253, 47
	s_andn2_b64 vcc, exec, s[2:3]
	s_mov_b64 s[26:27], s[18:19]
	v_readlane_b32 s9, v253, 37
	v_readlane_b32 s10, v253, 38
	v_readlane_b32 s11, v253, 39
	v_readlane_b32 s12, v253, 40
	v_readlane_b32 s13, v253, 41
	v_readlane_b32 s14, v253, 42
	v_readlane_b32 s15, v253, 43
	v_readlane_b32 s16, v253, 44
	v_readlane_b32 s17, v253, 45
	v_readlane_b32 s20, v253, 48
	v_readlane_b32 s21, v253, 49
	v_readlane_b32 s22, v253, 50
	v_readlane_b32 s23, v253, 51
	s_cbranch_vccnz .LBB0_1220
	s_waitcnt vmcnt(0)
	v_cmp_gt_u32_e32 vcc, 32, v0
	s_waitcnt vmcnt(0)
	s_barrier
	s_and_saveexec_b64 s[2:3], vcc
	s_cbranch_execz .LBB0_1219
	v_readlane_b32 s6, v253, 9
	s_lshl_b32 s6, s6, 8
	v_readlane_b32 s8, v253, 3
	v_readlane_b32 s9, v253, 4
	s_add_u32 s6, s8, s6
	s_addc_u32 s7, s9, 0
	s_add_u32 s6, s6, 0x20000
	s_addc_u32 s7, s7, 0
	s_add_i32 s101, s101, 0x100
	s_and_b32 s8, s101, 31
	s_lshr_b32 s9, s101, 8
	v_lshlrev_b32_e32 v1, 2, v0
	v_mov_b32_e32 v2, 1
	v_cmp_eq_u32_e32 vcc, s8, v0
	s_and_saveexec_b64 s[10:11], vcc
	global_atomic_add v1, v2, s[6:7]
	s_or_b64 exec, exec, s[10:11]
	buffer_inv sc1
	s_mov_b32 s8, 0
.Lxb_poll_4:
	global_load_dword v4, v1, s[6:7] sc1
	s_waitcnt vmcnt(0)
	v_cmp_gt_u32_e32 vcc, s9, v4
	s_nop 1
	s_cmp_eq_u64 vcc, 0
	s_cbranch_scc1 .Lxb_done_4
	s_add_i32 s8, s8, 1
	s_sleep 1
	s_cmp_lt_u32 s8, 0x40000
	s_cbranch_scc1 .Lxb_poll_4
.Lxb_done_4:
	s_waitcnt vmcnt(0)
.LBB0_1219:
	s_or_b64 exec, exec, s[2:3]
	s_barrier

.LBB0_1246:
	s_cmp_gt_i32 s89, 12
	s_cselect_b64 s[2:3], -1, 0
	s_and_b64 s[0:1], s[0:1], s[2:3]
	s_andn2_b64 vcc, exec, s[0:1]
	s_cbranch_vccnz .LBB0_1264
	s_waitcnt vmcnt(0)
	v_cmp_gt_u32_e32 vcc, 32, v0
	s_waitcnt vmcnt(0)
	s_barrier
	s_and_saveexec_b64 s[0:1], vcc
	s_cbranch_execz .LBB0_1263
	v_readlane_b32 s4, v253, 9
	s_lshl_b32 s4, s4, 8
	v_readlane_b32 s6, v253, 3
	v_readlane_b32 s7, v253, 4
	s_add_u32 s4, s6, s4
	s_addc_u32 s5, s7, 0
	s_add_u32 s4, s4, 0x20000
	s_addc_u32 s5, s5, 0
	s_add_i32 s101, s101, 0x100
	s_and_b32 s6, s101, 31
	s_lshr_b32 s7, s101, 8
	v_lshlrev_b32_e32 v1, 2, v0
	v_mov_b32_e32 v2, 1
	v_cmp_eq_u32_e32 vcc, s6, v0
	s_and_saveexec_b64 s[8:9], vcc
	global_atomic_add v1, v2, s[4:5]
	s_or_b64 exec, exec, s[8:9]
	buffer_inv sc1
	s_mov_b32 s6, 0

.Lxb_done_3:
	s_waitcnt vmcnt(0)
.LBB0_1263:
	s_or_b64 exec, exec, s[0:1]
	s_barrier

.LBB0_1274:
	s_cmp_gt_i32 s89, 13
	s_cselect_b64 s[0:1], -1, 0
	s_and_b64 s[2:3], s[6:7], s[0:1]
	s_andn2_b64 vcc, exec, s[2:3]
	s_cbranch_vccnz .LBB0_1292
	s_waitcnt vmcnt(0)
	v_cmp_gt_u32_e32 vcc, 32, v0
	s_waitcnt vmcnt(0) lgkmcnt(0)
	s_barrier
	s_and_saveexec_b64 s[2:3], vcc
	s_cbranch_execz .LBB0_1291
	v_readlane_b32 s4, v253, 9
	s_lshl_b32 s4, s4, 8
	v_readlane_b32 s6, v253, 3
	v_readlane_b32 s7, v253, 4
	s_add_u32 s4, s6, s4
	s_addc_u32 s5, s7, 0
	s_add_u32 s4, s4, 0x20000
	s_addc_u32 s5, s5, 0
	s_add_i32 s101, s101, 0x100
	s_and_b32 s6, s101, 31
	s_lshr_b32 s7, s101, 8
	v_lshlrev_b32_e32 v1, 2, v0
	v_mov_b32_e32 v2, 1
	v_cmp_eq_u32_e32 vcc, s6, v0
	s_and_saveexec_b64 s[8:9], vcc
	global_atomic_add v1, v2, s[4:5]
	s_or_b64 exec, exec, s[8:9]
	buffer_inv sc1
	s_mov_b32 s6, 0

.Lxb_done_2:
	s_waitcnt vmcnt(0)
.LBB0_1291:
	s_or_b64 exec, exec, s[2:3]
	s_barrier

.LBB0_1407:
	s_cmp_gt_i32 s89, 14
	s_cselect_b64 s[0:1], -1, 0
	s_and_b64 s[2:3], s[4:5], s[0:1]
	s_andn2_b64 vcc, exec, s[2:3]
	s_cbranch_vccnz .LBB0_1425
	s_waitcnt vmcnt(0)
	v_cmp_gt_u32_e32 vcc, 32, v0
	s_waitcnt vmcnt(0) lgkmcnt(0)
	s_barrier
	s_and_saveexec_b64 s[2:3], vcc
	s_cbranch_execz .LBB0_1424
	v_readlane_b32 s4, v253, 9
	s_lshl_b32 s4, s4, 8
	v_readlane_b32 s6, v253, 3
	v_readlane_b32 s7, v253, 4
	s_add_u32 s4, s6, s4
	s_addc_u32 s5, s7, 0
	s_add_u32 s4, s4, 0x20000
	s_addc_u32 s5, s5, 0
	s_add_i32 s101, s101, 0x100
	s_and_b32 s6, s101, 31
	s_lshr_b32 s7, s101, 8
	v_lshlrev_b32_e32 v1, 2, v0
	v_mov_b32_e32 v2, 1
	v_cmp_eq_u32_e32 vcc, s6, v0
	s_and_saveexec_b64 s[8:9], vcc
	global_atomic_add v1, v2, s[4:5]
	s_or_b64 exec, exec, s[8:9]
	buffer_inv sc1
	s_mov_b32 s6, 0

.Lxb_done_1:
	s_waitcnt vmcnt(0)
.LBB0_1424:
	s_or_b64 exec, exec, s[2:3]
	s_barrier

.LBB0_1451:
	s_cmp_gt_i32 s89, 15
	s_cselect_b64 s[2:3], -1, 0
	s_and_b64 s[0:1], s[0:1], s[2:3]
	s_andn2_b64 vcc, exec, s[0:1]
	s_cbranch_vccnz .LBB0_1469
	s_waitcnt vmcnt(0)
	v_cmp_gt_u32_e32 vcc, 32, v0
	s_waitcnt vmcnt(0) lgkmcnt(0)
	s_barrier
	s_and_saveexec_b64 s[0:1], vcc
	s_cbranch_execz .LBB0_1468
	v_readlane_b32 s4, v253, 9
	s_lshl_b32 s4, s4, 8
	v_readlane_b32 s6, v253, 3
	v_readlane_b32 s7, v253, 4
	s_add_u32 s4, s6, s4
	s_addc_u32 s5, s7, 0
	s_add_u32 s4, s4, 0x20000
	s_addc_u32 s5, s5, 0
	s_add_i32 s101, s101, 0x100
	s_and_b32 s6, s101, 31
	s_lshr_b32 s7, s101, 8
	v_lshlrev_b32_e32 v1, 2, v0
	v_mov_b32_e32 v2, 1
	v_cmp_eq_u32_e32 vcc, s6, v0
	s_and_saveexec_b64 s[8:9], vcc
	global_atomic_add v1, v2, s[4:5]
	s_or_b64 exec, exec, s[8:9]
	buffer_inv sc1
	s_mov_b32 s6, 0
.Lxb_poll_0:
	global_load_dword v3, v1, s[4:5] sc1
	s_waitcnt vmcnt(0)
	v_cmp_gt_u32_e32 vcc, s7, v3
	s_nop 1
	s_cmp_eq_u64 vcc, 0
	s_cbranch_scc1 .Lxb_done_0
	s_add_i32 s6, s6, 1
	s_sleep 1
	s_cmp_lt_u32 s6, 0x40000
	s_cbranch_scc1 .Lxb_poll_0
.Lxb_done_0:
	s_waitcnt vmcnt(0)
.LBB0_1468:
	s_or_b64 exec, exec, s[0:1]
	s_barrier
